# P1: half of the workgroups (bit 3 of the block id) start the phase about 3.5 us later so the two output write bursts do not coincide
# speedup vs baseline: 1.0037x; 1.0037x over previous
; #define SEAM(k) do { if (IN(k) && IN((k) + 1)) xcd_barrier(bar); } while (0)
;     __device__ __forceinline__ bool next(int i, Unit& u) const {
;         const long L = (long)i * G + c; if (L >= nwg) return false;
;         int wgid = (int)L; { const int q = nwg / NXCD, r = nwg % NXCD, xcd = wgid % NXCD, off = wgid / NXCD; wgid = (xcd < r ? xcd * (q + 1) : r * (q + 1) + (xcd - r) * q) + off; }
;         const int nig = WGM * nN, gid = wgid / nig, fm = gid * WGM, gsz = (nM - fm) < WGM ? (nM - fm) : WGM;
;         u.pm = fm + ((wgid % nig) % gsz); u.pn = (wgid % nig) / gsz; return true;
; __global__ void __launch_bounds__(512, 2) mega_fwd(Params p) {
;     ...
;     if (IN(0)) { prep_phase(p, lds); } SEAM(0);
;     if (IN(1)) { const EpiArgs E{ZB, 2048, nullptr, ST0, nullptr, nullptr, nullptr, nullptr, nullptr}; const bf16_t* W = (const bf16_t*)(ws + OFF_W_INE);
;         gemm_phase<EK_SCALE, EK_SCALE>(lds, XB, W, 64, 2048, 1024, E); } SEAM(1);
.LBB0_140:
	s_cmp_lt_i32 s34, 2
	s_cselect_b64 s[6:7], -1, 0
	s_add_u32 s62, s30, 0x2d60000
	s_addc_u32 s63, s31, 0
	s_add_u32 s64, s30, 0x4de0000
	s_addc_u32 s65, s31, 0
	s_and_b64 s[14:15], s[6:7], s[4:5]
	s_andn2_b64 vcc, exec, s[14:15]
	s_cbranch_vccnz .LBB0_206
	s_bitcmp1_b32 s2, 3
	s_cbranch_scc0 .Lmy_stag1
	s_sleep 127
.Lmy_stag1:
	s_cmpk_lt_i32 s2, 0x200
	s_cselect_b64 s[4:5], -1, 0
	s_cmpk_gt_i32 s2, 0x1ff
	v_readfirstlane_b32 s54, v0
	s_cbranch_scc1 .LBB0_147
	s_waitcnt lgkmcnt(0)
	s_ashr_i32 s3, s2, 31
	s_lshr_b32 s3, s3, 29
	s_add_i32 s9, s2, s3
	s_and_b32 s3, s9, -8
	s_sub_i32 s3, s2, s3
	s_cmp_gt_i32 s3, -1
	s_cbranch_scc0 .LBB0_144
	s_lshl_b32 s8, s3, 6
	s_ashr_i32 s6, s9, 3
	s_cbranch_execz .LBB0_145
	s_branch .LBB0_146
